# scan phase: one static s_setprio 1 for waves 4-7 (strategy 7.4 applied to the scan; reset at the attention phase)
# baseline (speedup 1.0000x reference)
; __device__ __forceinline__ int tid_opaque(int wv) { return wv * 64 + lane_fresh(); }
; __device__ __forceinline__ void scan_mfma(PP p, unsigned char* shm, int wv) {
;     const int tid_ = tid_opaque(wv); const int tid = tid_;
;     const int lane = tid & 63, n = wv, l31 = lane & 31, hl = lane >> 5;
;     constexpr int XS = 520;
;     bf16_t* xs = (bf16_t*)shm;
;     const bf16_t* proj = (const bf16_t*)(p->ws + WS_PROJ);
;     for (int item = blockIdx.x; item < 512 + 32; item += gridDim.x) {
;         const int id = item < 512 ? item : 512 + ((item - 512) >> 2);
;         const int quarter = item < 512 ? -1 : ((item - 512) & 3);
;         int rowbase, t0, seqlen; bool latent;
;         if (id < 512) { const int b = id >> 8, k = id & 255; t0 = 64 * k; rowbase = b * S + t0; seqlen = S; latent = true; }
;         else { const int j = id - 512, b = j >> 2, k = j & 3; t0 = 64 * k; rowbase = NLAT + b * LC + t0; seqlen = LC; latent = false; }
;         const int seqbase = rowbase - t0;
;         ScanW w0, w1;
.LBB0_327:
	s_or_b64 exec, exec, s[4:5]
	s_mov_b64 s[8:9], s[0:1]
	s_mov_b32 s27, -1
	s_mov_b32 s6, -1
	s_cmpk_gt_i32 s2, 0x21f
	s_waitcnt lgkmcnt(0)
	s_barrier
	s_cbranch_scc1 .LBB0_453
	s_load_dwordx2 s[4:5], s[8:9], 0xd0
	s_mov_b32 s17, 0
	v_mbcnt_lo_u32_b32 v0, s6, 0
	v_mbcnt_hi_u32_b32 v0, s6, v0
	v_and_b32_e32 v148, 31, v0
	s_waitcnt lgkmcnt(0)
	s_add_u32 s10, s4, 0x9c77000
	s_addc_u32 s11, s5, 0
	s_add_u32 s12, s4, 0x1c72000
	s_addc_u32 s13, s5, 0
	s_add_u32 s22, s4, 0x1600000
	s_addc_u32 s23, s5, 0
	s_lshl_b64 s[6:7], s[16:17], 13
	s_add_u32 s14, s22, s6
	s_addc_u32 s15, s23, s7
	s_add_i32 s6, s16, 8
	s_mov_b32 s7, s17
	s_lshl_b64 s[6:7], s[6:7], 13
	s_add_u32 s18, s22, s6
	s_addc_u32 s19, s23, s7
	s_add_i32 s6, s16, 16
	s_mov_b32 s7, s17
	s_add_i32 s50, s33, 0x200
	s_lshl_b64 s[6:7], s[6:7], 13
	s_add_u32 s20, s22, s6
	s_addc_u32 s21, s23, s7
	s_add_i32 s16, s16, 24
	s_lshl_b64 s[6:7], s[16:17], 13
	s_add_u32 s16, s22, s6
	s_addc_u32 s17, s23, s7
	s_lshl_b32 s6, s33, 1
	s_add_i32 s6, s6, 0
	s_add_u32 s52, s4, 0x5c77000
	s_addc_u32 s53, s5, 0
	v_lshrrev_b32_e32 v1, 5, v0
	v_bfe_u32 v0, v0, 5, 1
	s_add_u32 s54, s4, 0x165a000
	v_lshlrev_b32_e32 v149, 3, v0
	v_lshl_add_u32 v32, v0, 4, s6
	s_movk_i32 s51, 0x410
	v_mul_u32_u24_e32 v151, 0x1040, v0
	v_lshl_or_b32 v1, v1, 2, 8
	v_cmp_eq_u32_e64 s[6:7], 0, v0
	v_lshlrev_b32_e32 v153, 11, v0
	s_addc_u32 s55, s5, 0
	v_mov_b32_e32 v0, 0xffffe390
	v_mul_u32_u24_e32 v33, 0x410, v148
	v_mul_u32_u24_e32 v152, 0x410, v1
	v_lshlrev_b32_e32 v157, 9, v1
	v_mad_u32_u24 v185, v1, s51, v0
	s_add_u32 s57, s4, 0x3c77000
	v_mov_b32_e32 v1, 0
	s_addc_u32 s58, s5, 0
	v_mov_b32_e32 v2, v1
	v_mov_b32_e32 v3, v1
	v_mov_b32_e32 v4, v1
	v_mov_b32_e32 v5, v1
	v_mov_b32_e32 v6, v1
	v_mov_b32_e32 v7, v1
	v_mov_b32_e32 v8, v1
	v_mov_b32_e32 v9, v1
	v_mov_b32_e32 v10, v1
	v_mov_b32_e32 v11, v1
	v_mov_b32_e32 v12, v1
	v_mov_b32_e32 v13, v1
	v_mov_b32_e32 v14, v1
	v_mov_b32_e32 v15, v1
	v_mov_b32_e32 v16, v1
	v_mov_b32_e32 v17, v1
	v_mov_b32_e32 v18, v1
	v_mov_b32_e32 v19, v1
	v_mov_b32_e32 v20, v1
	v_mov_b32_e32 v21, v1
	v_mov_b32_e32 v22, v1
	v_mov_b32_e32 v23, v1
	v_mov_b32_e32 v24, v1
	v_mov_b32_e32 v25, v1
	v_mov_b32_e32 v26, v1
	v_mov_b32_e32 v27, v1
	v_mov_b32_e32 v28, v1
	v_mov_b32_e32 v29, v1
	v_mov_b32_e32 v30, v1
	v_mov_b32_e32 v31, v1
	v_add_u32_e32 v187, v32, v33
	v_mbcnt_lo_u32_b32 v32, -1, 0
	s_add_u32 s59, s4, 0x7c77000
	v_mov_b32_e32 v0, v1
	v_mbcnt_hi_u32_b32 v188, -1, v32
	v_mov_b64_e32 v[32:33], v[30:31]
	v_or_b32_e32 v150, s33, v148
	v_or_b32_e32 v160, 0x1600, v153
	v_or_b32_e32 v161, 0x2000, v153
	v_or_b32_e32 v162, 0x2200, v153
	v_or_b32_e32 v163, 0x2400, v153
	v_or_b32_e32 v164, 0x2600, v153
	v_or_b32_e32 v165, 0x3000, v153
	v_or_b32_e32 v166, 0x3200, v153
	v_or_b32_e32 v167, 0x3400, v153
	v_or_b32_e32 v168, 0x3600, v153
	v_or_b32_e32 v169, 0x4000, v153
	v_or_b32_e32 v170, 0x4200, v153
	v_or_b32_e32 v171, 0x4400, v153
	v_or_b32_e32 v172, 0x4600, v153
	v_or_b32_e32 v173, 0x5000, v153
	v_or_b32_e32 v174, 0x5200, v153
	v_or_b32_e32 v175, 0x5400, v153
	v_or_b32_e32 v176, 0x5600, v153
	v_or_b32_e32 v177, 0x6000, v153
	v_or_b32_e32 v178, 0x6200, v153
	v_or_b32_e32 v179, 0x6400, v153
	v_or_b32_e32 v180, 0x6600, v153
	v_or_b32_e32 v181, 0x7000, v153
	v_or_b32_e32 v182, 0x7200, v153
	v_or_b32_e32 v183, 0x7400, v153
	v_or_b32_e32 v184, 0x7600, v153
	s_addc_u32 s60, s5, 0
	s_movk_i32 s61, 0xc0
	s_movk_i32 s64, 0x100
	s_add_i32 s65, 0, 0x10400
	s_movk_i32 s66, 0x10c0
	s_movk_i32 s67, 0xe00
	s_movk_i32 s68, 0xec0
	s_movk_i32 s69, 0xcc0
	s_movk_i32 s70, 0xac0
	s_movk_i32 s71, 0x8c0
	s_movk_i32 s72, 0x6c0
	s_movk_i32 s73, 0x4c0
	s_movk_i32 s74, 0x2c0
	s_movk_i32 s75, 0x1000
	v_mov_b32_e32 v186, 0x3d2aaaab
	s_mov_b32 s76, 0xbdcccccd
	s_movk_i32 s77, 0x7fff
	s_mov_b32 s78, s2
	s_cmpk_lt_u32 s33, 0x100
	s_cbranch_scc1 .Lsp_scan
	s_setprio 1
.Lsp_scan:
	v_mov_b64_e32 v[30:31], v[28:29]
	v_mov_b64_e32 v[28:29], v[26:27]
	v_mov_b64_e32 v[26:27], v[24:25]
	v_mov_b64_e32 v[24:25], v[22:23]
	v_mov_b64_e32 v[22:23], v[20:21]
	v_mov_b64_e32 v[20:21], v[18:19]
	v_mov_b64_e32 v[18:19], v[16:17]
	v_mov_b64_e32 v[16:17], v[14:15]
	v_mov_b64_e32 v[14:15], v[12:13]
	v_mov_b64_e32 v[12:13], v[10:11]
	v_mov_b64_e32 v[10:11], v[8:9]
	v_mov_b64_e32 v[8:9], v[6:7]
	v_mov_b64_e32 v[6:7], v[4:5]
	v_mov_b64_e32 v[4:5], v[2:3]
	v_mov_b64_e32 v[2:3], v[0:1]
	s_branch .LBB0_330

; __device__ __forceinline__ int tid_opaque(int wv) { return wv * 64 + lane_fresh(); }
; __device__ __forceinline__ void attn_mfma(PP p, unsigned char* shm, int wv) {
;     const int tid = tid_opaque(wv);
;     const int lane = tid & 63, wave = wv, l31 = lane & 31, hl = lane >> 5;
;     const bf16_t* proj = (const bf16_t*)(p->ws + WS_PROJ);
;     bf16_t* att = (bf16_t*)(p->ws + WS_ATT);
;     const float L2E = 1.4426950408889634f;
;     const float SC2 = 0.125f * L2E;
;     for (int item = blockIdx.x; item < 512; item += gridDim.x) {
;         const int hk = item & 1, qb = (item >> 1) & 127, b = item >> 8;
;         const int g = wave >> 1, qh = wave & 1, hq = hk * 4 + g;
;         const int qrow0 = b * S + 128 * qb + 64 * qh;
.LBB0_453:
	s_setprio 0
	s_cmpk_lt_i32 s2, 0x200
	s_mov_b64 s[4:5], s[0:1]
	s_cselect_b64 s[22:23], -1, 0
	s_cmpk_gt_i32 s2, 0x1ff
	s_cbranch_scc1 .LBB0_489
	s_mov_b32 s97, 0
	s_load_dwordx2 s[14:15], s[4:5], 0xd0
	s_load_dwordx2 s[8:9], s[4:5], 0x78
	v_mbcnt_lo_u32_b32 v1, s27, 0
	v_mbcnt_hi_u32_b32 v1, s27, v1
	v_mov_b32_e32 v0, 0
	s_waitcnt lgkmcnt(0)
	s_add_u32 s4, s14, 0x9c77000
	v_bfe_u32 v6, v1, 5, 1
	v_and_b32_e32 v8, 31, v1
	s_addc_u32 s5, s15, 0
	v_add_u32_e32 v5, s33, v1
	s_bfe_u32 s6, s56, 0x10006
	v_lshlrev_b32_e32 v2, 3, v6
	v_mov_b32_e32 v3, v0
	v_lshlrev_b32_e32 v1, 3, v1
	s_lshr_b32 s27, s56, 7
	s_lshl_b32 s16, s6, 6
	v_cmp_eq_u32_e32 vcc, 0, v6
	v_and_b32_e32 v162, 56, v1
	v_lshlrev_b32_e32 v9, 4, v6
	v_lshlrev_b32_e32 v181, 2, v6
	v_lshl_add_u64 v[6:7], s[14:15], 0, v[2:3]
	s_mov_b64 s[14:15], 0x1c77000
	v_lshlrev_b32_e32 v4, 1, v162
	s_bitcmp1_b32 s56, 6
	v_lshl_add_u64 v[164:165], v[6:7], 0, s[14:15]
	v_ashrrev_i32_e32 v182, 3, v5
	v_add_u32_e32 v3, 0x200, v5
	v_mul_u32_u24_e32 v7, 0x108, v8
	v_mov_b32_e32 v5, v0
	v_add_u32_e32 v1, 0, v4
	s_cselect_b64 s[10:11], -1, 0
	s_cmp_eq_u32 s6, 0
	v_ashrrev_i32_e32 v183, 3, v3
	s_movk_i32 s6, 0x90
	v_lshl_add_u64 v[166:167], s[4:5], 0, v[4:5]
	v_add3_u32 v4, v7, v2, 0
	v_mul_lo_u32 v184, v182, s6
	v_mul_lo_u32 v186, v183, s6
	v_add_u32_e32 v187, 0x4800, v4
	v_mul_u32_u24_e32 v4, 0x90, v8
	v_lshl_add_u32 v3, v182, 1, 0
	v_mul_u32_u24_e32 v185, 0x108, v162
	v_lshl_add_u32 v6, v183, 1, 0
	v_add3_u32 v188, v4, v9, 0
	v_sub_u32_e32 v4, v181, v8
	v_add_u32_e32 v190, v1, v184
	v_add_u32_e32 v192, v1, v186
	v_mbcnt_lo_u32_b32 v1, -1, 0
	s_mov_b32 s7, 0
	v_cndmask_b32_e64 v163, 0, 1.0, vcc
	s_cselect_b64 s[12:13], -1, 0
	v_or_b32_e32 v180, s16, v8
	v_subrev_u32_e32 v189, s16, v4
	s_movk_i32 s30, 0xe00
	v_mov_b64_e32 v[168:169], s[4:5]
	v_lshlrev_b32_e32 v170, 1, v2
	v_mov_b32_e32 v171, v0
	v_lshlrev_b32_e32 v172, 1, v162
	v_mov_b32_e32 v173, v0
	v_add_u32_e32 v191, v3, v185
	v_add_u32_e32 v193, v6, v185
	s_mov_b32 s31, 0x3e38aa3b
	v_mov_b32_e32 v194, 0xf149f2ca
	v_mbcnt_hi_u32_b32 v195, -1, v1
	s_mov_b32 s34, s2
	s_branch .LBB0_456
